# attention loops: s_setprio 3 during the MFMA block, 0 during the softmax block (both wave groups)
# speedup vs baseline: 1.0057x; 1.0018x over previous
.LBB0_599:
	s_setprio 3
	s_mov_b32 s75, s74
	s_mov_b32 s74, s0
	v_add_u32_e32 v238, s74, v193
	ds_read_b64_tr_b16 v[194:195], v238 offset:0
	ds_read_b64_tr_b16 v[196:197], v238 offset:0x800
	ds_read_b64_tr_b16 v[198:199], v238 offset:0x1000
	ds_read_b64_tr_b16 v[200:201], v238 offset:0x1800
	ds_read_b64_tr_b16 v[202:203], v238 offset:0x2000
	ds_read_b64_tr_b16 v[204:205], v238 offset:0x2800
	ds_read_b64_tr_b16 v[206:207], v238 offset:0x3000
	ds_read_b64_tr_b16 v[208:209], v238 offset:0x3800
	ds_read_b128 v[82:85], v188 offset:40960
	ds_read_b128 v[210:213], v188 offset:45056
	ds_read_b128 v[214:217], v189 offset:40960
	ds_read_b128 v[218:221], v189 offset:45056
	ds_read_b128 v[222:225], v190 offset:40960
	ds_read_b128 v[226:229], v190 offset:45056
	ds_read_b128 v[230:233], v191 offset:40960
	ds_read_b128 v[234:237], v191 offset:45056
	s_waitcnt lgkmcnt(0)
	v_mfma_f32_32x32x16_bf16 v[98:113], v[82:85], v[126:129], v[66:81]
	v_mfma_f32_32x32x16_bf16 v[82:97], v[210:213], v[126:129], v[66:81]
	v_mfma_f32_32x32x16_bf16 v[98:113], v[214:217], v[122:125], v[98:113]
	v_mfma_f32_32x32x16_bf16 v[82:97], v[218:221], v[122:125], v[82:97]
	v_mfma_f32_32x32x16_bf16 v[98:113], v[222:225], v[118:121], v[98:113]
	v_mfma_f32_32x32x16_bf16 v[82:97], v[226:229], v[118:121], v[82:97]
	v_mfma_f32_32x32x16_bf16 v[98:113], v[230:233], v[114:117], v[98:113]
	v_mfma_f32_32x32x16_bf16 v[82:97], v[234:237], v[114:117], v[82:97]
	ds_read_b64_tr_b16 v[210:211], v238 offset:0x200
	ds_read_b64_tr_b16 v[212:213], v238 offset:0xa00
	ds_read_b64_tr_b16 v[214:215], v238 offset:0x1200
	ds_read_b64_tr_b16 v[216:217], v238 offset:0x1a00
	ds_read_b64_tr_b16 v[218:219], v238 offset:0x2200
	ds_read_b64_tr_b16 v[220:221], v238 offset:0x2a00
	ds_read_b64_tr_b16 v[222:223], v238 offset:0x3200
	ds_read_b64_tr_b16 v[224:225], v238 offset:0x3a00
	s_waitcnt lgkmcnt(8)
	v_mfma_f32_32x32x16_bf16 v[50:65], v[142:145], v[194:197], v[50:65]
	v_mfma_f32_32x32x16_bf16 v[50:65], v[138:141], v[198:201], v[50:65]
	v_mfma_f32_32x32x16_bf16 v[50:65], v[134:137], v[202:205], v[50:65]
	v_mfma_f32_32x32x16_bf16 v[50:65], v[130:133], v[206:209], v[50:65]
	ds_read_b64_tr_b16 v[194:195], v238 offset:0x400
	ds_read_b64_tr_b16 v[196:197], v238 offset:0xc00
	ds_read_b64_tr_b16 v[198:199], v238 offset:0x1400
	ds_read_b64_tr_b16 v[200:201], v238 offset:0x1c00
	ds_read_b64_tr_b16 v[202:203], v238 offset:0x2400
	ds_read_b64_tr_b16 v[204:205], v238 offset:0x2c00
	ds_read_b64_tr_b16 v[206:207], v238 offset:0x3400
	ds_read_b64_tr_b16 v[208:209], v238 offset:0x3c00
	s_waitcnt lgkmcnt(8)
	v_mfma_f32_32x32x16_bf16 v[34:49], v[142:145], v[210:213], v[34:49]
	v_mfma_f32_32x32x16_bf16 v[34:49], v[138:141], v[214:217], v[34:49]
	v_mfma_f32_32x32x16_bf16 v[34:49], v[134:137], v[218:221], v[34:49]
	v_mfma_f32_32x32x16_bf16 v[34:49], v[130:133], v[222:225], v[34:49]
	ds_read_b64_tr_b16 v[210:211], v238 offset:0x600
	ds_read_b64_tr_b16 v[212:213], v238 offset:0xe00
	ds_read_b64_tr_b16 v[214:215], v238 offset:0x1600
	ds_read_b64_tr_b16 v[216:217], v238 offset:0x1e00
	ds_read_b64_tr_b16 v[218:219], v238 offset:0x2600
	ds_read_b64_tr_b16 v[220:221], v238 offset:0x2e00
	ds_read_b64_tr_b16 v[222:223], v238 offset:0x3600
	ds_read_b64_tr_b16 v[224:225], v238 offset:0x3e00
	s_waitcnt lgkmcnt(8)
	v_mfma_f32_32x32x16_bf16 v[18:33], v[142:145], v[194:197], v[18:33]
	v_mfma_f32_32x32x16_bf16 v[18:33], v[138:141], v[198:201], v[18:33]
	v_mfma_f32_32x32x16_bf16 v[18:33], v[134:137], v[202:205], v[18:33]
	v_mfma_f32_32x32x16_bf16 v[18:33], v[130:133], v[206:209], v[18:33]
	s_waitcnt lgkmcnt(0)
	v_mfma_f32_32x32x16_bf16 v[2:17], v[142:145], v[210:213], v[2:17]
	v_mfma_f32_32x32x16_bf16 v[2:17], v[138:141], v[214:217], v[2:17]
	v_mfma_f32_32x32x16_bf16 v[2:17], v[134:137], v[218:221], v[2:17]
	v_mfma_f32_32x32x16_bf16 v[2:17], v[130:133], v[222:225], v[2:17]
	s_and_b64 vcc, exec, s[6:7]
	s_cbranch_vccnz .LBB0_601
	s_waitcnt vmcnt(1)
.LBB0_601:
	s_and_b64 vcc, exec, s[2:3]
	s_barrier
	s_setprio 0
	s_cbranch_vccnz .LBB0_603
	v_lshl_add_u64 v[130:131], s[58:59], 0, v[150:151]
	s_add_u32 s58, s58, 0x100000
	s_mov_b32 m0, s93
	s_addc_u32 s59, s59, 0
	s_add_i32 s0, s94, s12
	global_load_lds_dwordx4 v[130:131], off
	v_lshl_add_u64 v[130:131], s[60:61], 0, v[170:171]
	s_add_i32 m0, s0, 0xc000
	s_nop 0
	global_load_lds_dwordx4 v[130:131], off
	s_add_i32 m0, s0, 0xc400
	v_lshl_add_u64 v[130:131], s[60:61], 0, v[172:173]
	s_add_u32 s60, s60, 0x100000
	s_addc_u32 s61, s61, 0
	s_cmpk_lt_i32 s95, 0x84
	v_lshl_add_u64 v[130:131], v[130:131], 0, s[24:25]
	s_cselect_b32 s1, 0, -1
	s_cselect_b32 s0, 0, 0xffd00000
	global_load_lds_dwordx4 v[130:131], off
	v_lshl_add_u64 v[130:131], v[174:175], 0, s[0:1]
	s_add_i32 s0, s97, 0
	s_add_i32 m0, s0, 0x18800
	v_lshl_add_u64 v[174:175], v[174:175], 0, s[20:21]
	global_load_lds_dword v[130:131], off
	s_add_i32 s95, s95, 1

.LBB0_612:
	s_barrier
	s_setprio 3
	v_add_u32_e32 v197, s75, v193
	ds_read_b64_tr_b16 v[198:199], v197 offset:0
	ds_read_b64_tr_b16 v[200:201], v197 offset:0x800
	ds_read_b64_tr_b16 v[202:203], v197 offset:0x1000
	ds_read_b64_tr_b16 v[204:205], v197 offset:0x1800
	ds_read_b64_tr_b16 v[206:207], v197 offset:0x2000
	ds_read_b64_tr_b16 v[208:209], v197 offset:0x2800
	ds_read_b64_tr_b16 v[210:211], v197 offset:0x3000
	ds_read_b64_tr_b16 v[212:213], v197 offset:0x3800
	ds_read_b128 v[82:85], v188 offset:32768
	ds_read_b128 v[214:217], v188 offset:36864
	ds_read_b128 v[218:221], v189 offset:32768
	ds_read_b128 v[222:225], v189 offset:36864
	ds_read_b128 v[226:229], v190 offset:32768
	ds_read_b128 v[230:233], v190 offset:36864
	ds_read_b128 v[234:237], v191 offset:32768
	ds_read_b128 v[238:241], v191 offset:36864
	s_waitcnt lgkmcnt(0)
	v_mfma_f32_32x32x16_bf16 v[98:113], v[82:85], v[126:129], v[66:81]
	v_mfma_f32_32x32x16_bf16 v[82:97], v[214:217], v[126:129], v[66:81]
	v_mfma_f32_32x32x16_bf16 v[98:113], v[218:221], v[122:125], v[98:113]
	v_mfma_f32_32x32x16_bf16 v[82:97], v[222:225], v[122:125], v[82:97]
	v_mfma_f32_32x32x16_bf16 v[98:113], v[226:229], v[118:121], v[98:113]
	v_mfma_f32_32x32x16_bf16 v[82:97], v[230:233], v[118:121], v[82:97]
	v_mfma_f32_32x32x16_bf16 v[98:113], v[234:237], v[114:117], v[98:113]
	v_mfma_f32_32x32x16_bf16 v[82:97], v[238:241], v[114:117], v[82:97]
	ds_read_b64_tr_b16 v[214:215], v197 offset:0x200
	ds_read_b64_tr_b16 v[216:217], v197 offset:0xa00
	ds_read_b64_tr_b16 v[218:219], v197 offset:0x1200
	ds_read_b64_tr_b16 v[220:221], v197 offset:0x1a00
	ds_read_b64_tr_b16 v[222:223], v197 offset:0x2200
	ds_read_b64_tr_b16 v[224:225], v197 offset:0x2a00
	ds_read_b64_tr_b16 v[226:227], v197 offset:0x3200
	ds_read_b64_tr_b16 v[228:229], v197 offset:0x3a00
	s_waitcnt lgkmcnt(8)
	v_mfma_f32_32x32x16_bf16 v[50:65], v[142:145], v[198:201], v[50:65]
	v_mfma_f32_32x32x16_bf16 v[50:65], v[138:141], v[202:205], v[50:65]
	v_mfma_f32_32x32x16_bf16 v[50:65], v[134:137], v[206:209], v[50:65]
	v_mfma_f32_32x32x16_bf16 v[50:65], v[130:133], v[210:213], v[50:65]
	ds_read_b64_tr_b16 v[198:199], v197 offset:0x400
	ds_read_b64_tr_b16 v[200:201], v197 offset:0xc00
	ds_read_b64_tr_b16 v[202:203], v197 offset:0x1400
	ds_read_b64_tr_b16 v[204:205], v197 offset:0x1c00
	ds_read_b64_tr_b16 v[206:207], v197 offset:0x2400
	ds_read_b64_tr_b16 v[208:209], v197 offset:0x2c00
	ds_read_b64_tr_b16 v[210:211], v197 offset:0x3400
	ds_read_b64_tr_b16 v[212:213], v197 offset:0x3c00
	s_waitcnt lgkmcnt(8)
	v_mfma_f32_32x32x16_bf16 v[34:49], v[142:145], v[214:217], v[34:49]
	v_mfma_f32_32x32x16_bf16 v[34:49], v[138:141], v[218:221], v[34:49]
	v_mfma_f32_32x32x16_bf16 v[34:49], v[134:137], v[222:225], v[34:49]
	v_mfma_f32_32x32x16_bf16 v[34:49], v[130:133], v[226:229], v[34:49]
	ds_read_b64_tr_b16 v[214:215], v197 offset:0x600
	ds_read_b64_tr_b16 v[216:217], v197 offset:0xe00
	ds_read_b64_tr_b16 v[218:219], v197 offset:0x1600
	ds_read_b64_tr_b16 v[220:221], v197 offset:0x1e00
	ds_read_b64_tr_b16 v[222:223], v197 offset:0x2600
	ds_read_b64_tr_b16 v[224:225], v197 offset:0x2e00
	ds_read_b64_tr_b16 v[226:227], v197 offset:0x3600
	ds_read_b64_tr_b16 v[228:229], v197 offset:0x3e00
	s_waitcnt lgkmcnt(8)
	v_mfma_f32_32x32x16_bf16 v[18:33], v[142:145], v[198:201], v[18:33]
	v_mfma_f32_32x32x16_bf16 v[18:33], v[138:141], v[202:205], v[18:33]
	v_mfma_f32_32x32x16_bf16 v[18:33], v[134:137], v[206:209], v[18:33]
	v_mfma_f32_32x32x16_bf16 v[18:33], v[130:133], v[210:213], v[18:33]
	s_waitcnt lgkmcnt(0)
	v_mfma_f32_32x32x16_bf16 v[2:17], v[142:145], v[214:217], v[2:17]
	v_mfma_f32_32x32x16_bf16 v[2:17], v[138:141], v[218:221], v[2:17]
	v_mfma_f32_32x32x16_bf16 v[2:17], v[134:137], v[222:225], v[2:17]
	v_mfma_f32_32x32x16_bf16 v[2:17], v[130:133], v[226:229], v[2:17]
	s_and_b64 vcc, exec, s[6:7]
	s_cbranch_vccnz .LBB0_614
	s_waitcnt vmcnt(1)
.LBB0_614:
	s_and_b64 vcc, exec, s[2:3]
	s_barrier
	s_setprio 0
	s_cbranch_vccnz .LBB0_616
	s_add_i32 m0, s92, 0xa000
	v_lshl_add_u64 v[130:131], s[58:59], 0, v[150:151]
	s_add_u32 s58, s58, 0x100000
	s_addc_u32 s59, s59, 0
	s_add_i32 s0, s94, s74
	global_load_lds_dwordx4 v[130:131], off
	v_lshl_add_u64 v[130:131], s[60:61], 0, v[170:171]
	s_add_i32 m0, s0, 0xc000
	s_nop 0
	global_load_lds_dwordx4 v[130:131], off
	s_add_i32 m0, s0, 0xc400
	v_lshl_add_u64 v[130:131], s[60:61], 0, v[172:173]
	s_add_u32 s60, s60, 0x100000
	s_addc_u32 s61, s61, 0
	s_cmpk_lt_i32 s95, 0x84
	v_lshl_add_u64 v[130:131], v[130:131], 0, s[24:25]
	s_cselect_b32 s1, 0, -1
	s_cselect_b32 s0, 0, 0xffd00000
	global_load_lds_dwordx4 v[130:131], off
	v_lshl_add_u64 v[130:131], v[174:175], 0, s[0:1]
	s_add_i32 s0, s97, 0
	s_add_i32 m0, s0, 0x18800
	v_lshl_add_u64 v[174:175], v[174:175], 0, s[20:21]
	global_load_lds_dword v[130:131], off
	s_add_i32 s95, s95, 1

.LBB0_666:
	s_setprio 3
	v_add_u32_e32 v189, v187, v160
	v_add_u32_e32 v190, v187, v162
	v_add_u32_e32 v191, v187, v164
	v_add_u32_e32 v192, v187, v166
	ds_read_b128 v[66:69], v189 offset:16384
	ds_read_b128 v[70:73], v189 offset:24576
	ds_read_b128 v[194:197], v190 offset:16384
	ds_read_b128 v[198:201], v190 offset:24576
	ds_read_b128 v[202:205], v191 offset:16384
	ds_read_b128 v[206:209], v191 offset:24576
	ds_read_b128 v[210:213], v192 offset:16384
	ds_read_b128 v[214:217], v192 offset:24576
	s_mov_b32 s12, s94
	s_mov_b32 s94, s8
	v_add_u32_e32 v250, s94, v185
	s_waitcnt lgkmcnt(0)
	v_mfma_f32_32x32x16_bf16 v[82:97], v[66:69], v[114:117], 0
	v_mfma_f32_32x32x16_bf16 v[66:81], v[70:73], v[114:117], 0
	v_mfma_f32_32x32x16_bf16 v[82:97], v[194:197], v[110:113], v[82:97]
	v_mfma_f32_32x32x16_bf16 v[66:81], v[198:201], v[110:113], v[66:81]
	v_add_u32_e32 v193, v187, v168
	v_add_u32_e32 v194, v187, v170
	ds_read_b128 v[198:201], v193 offset:24576
	ds_read_b128 v[218:221], v194 offset:16384
	ds_read_b128 v[222:225], v194 offset:24576
	ds_read_b128 v[226:229], v193 offset:16384
	ds_read_b128 v[230:233], v159
	v_mfma_f32_32x32x16_bf16 v[82:97], v[202:205], v[106:109], v[82:97]
	v_mfma_f32_32x32x16_bf16 v[66:81], v[206:209], v[106:109], v[66:81]
	v_mfma_f32_32x32x16_bf16 v[82:97], v[210:213], v[102:105], v[82:97]
	v_mfma_f32_32x32x16_bf16 v[66:81], v[214:217], v[102:105], v[66:81]
	v_add_u32_e32 v195, v187, v172
	v_add_u32_e32 v196, v187, v174
	ds_read_b128 v[202:205], v195 offset:16384
	ds_read_b128 v[206:209], v195 offset:24576
	ds_read_b128 v[210:213], v196 offset:16384
	ds_read_b128 v[214:217], v196 offset:24576
	ds_read_b128 v[234:237], v159 offset:1024
	ds_read_b128 v[238:241], v159 offset:2048
	s_waitcnt lgkmcnt(0)
	v_mfma_f32_32x32x16_bf16 v[82:97], v[226:229], v[98:101], v[82:97]
	v_mfma_f32_32x32x16_bf16 v[66:81], v[198:201], v[98:101], v[66:81]
	v_mfma_f32_32x32x16_bf16 v[82:97], v[218:221], v[230:233], v[82:97]
	v_mfma_f32_32x32x16_bf16 v[66:81], v[222:225], v[230:233], v[66:81]
	v_add_u32_e32 v197, v188, v177
	v_add_u32_e32 v198, v188, v179
	ds_read_b128 v[218:221], v197 offset:40960
	ds_read_b128 v[222:225], v197 offset:45056
	ds_read_b128 v[226:229], v198 offset:40960
	ds_read_b128 v[230:233], v198 offset:45056
	ds_read_b128 v[242:245], v159 offset:3072
	ds_read_b128 v[246:249], v159 offset:4096
	v_mfma_f32_32x32x16_bf16 v[82:97], v[202:205], v[234:237], v[82:97]
	v_mfma_f32_32x32x16_bf16 v[66:81], v[206:209], v[234:237], v[66:81]
	v_mfma_f32_32x32x16_bf16 v[82:97], v[210:213], v[238:241], v[82:97]
	v_mfma_f32_32x32x16_bf16 v[66:81], v[214:217], v[238:241], v[66:81]
	v_add_u32_e32 v199, v188, v181
	v_add_u32_e32 v200, v188, v183
	ds_read_b128 v[202:205], v199 offset:40960
	ds_read_b128 v[206:209], v199 offset:45056
	ds_read_b128 v[210:213], v200 offset:40960
	ds_read_b128 v[214:217], v200 offset:45056
	ds_read_b128 v[234:237], v159 offset:5120
	ds_read_b128 v[238:241], v159 offset:6144
	s_waitcnt lgkmcnt(0)
	v_mfma_f32_32x32x16_bf16 v[82:97], v[218:221], v[242:245], v[82:97]
	v_mfma_f32_32x32x16_bf16 v[66:81], v[222:225], v[242:245], v[66:81]
	v_mfma_f32_32x32x16_bf16 v[82:97], v[226:229], v[246:249], v[82:97]
	v_mfma_f32_32x32x16_bf16 v[66:81], v[230:233], v[246:249], v[66:81]
	v_mfma_f32_32x32x16_bf16 v[82:97], v[202:205], v[234:237], v[82:97]
	v_mfma_f32_32x32x16_bf16 v[66:81], v[206:209], v[234:237], v[66:81]
	v_mfma_f32_32x32x16_bf16 v[82:97], v[210:213], v[238:241], v[82:97]
	v_mfma_f32_32x32x16_bf16 v[66:81], v[214:217], v[238:241], v[66:81]
	ds_read_b64_tr_b16 v[202:203], v250 offset:0
	ds_read_b64_tr_b16 v[204:205], v250 offset:0x800
	ds_read_b64_tr_b16 v[206:207], v250 offset:0x1000
	ds_read_b64_tr_b16 v[208:209], v250 offset:0x1800
	ds_read_b64_tr_b16 v[210:211], v250 offset:0x2000
	ds_read_b64_tr_b16 v[212:213], v250 offset:0x2800
	ds_read_b64_tr_b16 v[214:215], v250 offset:0x3000
	ds_read_b64_tr_b16 v[216:217], v250 offset:0x3800
	ds_read_b64_tr_b16 v[218:219], v250 offset:0x200
	ds_read_b64_tr_b16 v[220:221], v250 offset:0xa00
	ds_read_b64_tr_b16 v[222:223], v250 offset:0x1200
	ds_read_b64_tr_b16 v[224:225], v250 offset:0x1a00
	ds_read_b64_tr_b16 v[226:227], v250 offset:0x2200
	ds_read_b64_tr_b16 v[228:229], v250 offset:0x2a00
	ds_read_b64_tr_b16 v[230:231], v250 offset:0x3200
	ds_read_b64_tr_b16 v[232:233], v250 offset:0x3a00
	s_waitcnt lgkmcnt(8)
	s_nop 0
	v_mfma_f32_32x32x16_bf16 v[50:65], v[130:133], v[202:205], v[50:65]
	v_mfma_f32_32x32x16_bf16 v[50:65], v[126:129], v[206:209], v[50:65]
	v_mfma_f32_32x32x16_bf16 v[50:65], v[122:125], v[210:213], v[50:65]
	v_mfma_f32_32x32x16_bf16 v[50:65], v[118:121], v[214:217], v[50:65]
	ds_read_b64_tr_b16 v[202:203], v250 offset:0x400
	ds_read_b64_tr_b16 v[204:205], v250 offset:0xc00
	ds_read_b64_tr_b16 v[206:207], v250 offset:0x1400
	ds_read_b64_tr_b16 v[208:209], v250 offset:0x1c00
	ds_read_b64_tr_b16 v[210:211], v250 offset:0x2400
	ds_read_b64_tr_b16 v[212:213], v250 offset:0x2c00
	ds_read_b64_tr_b16 v[214:215], v250 offset:0x3400
	ds_read_b64_tr_b16 v[216:217], v250 offset:0x3c00
	s_waitcnt lgkmcnt(8)
	v_mfma_f32_32x32x16_bf16 v[34:49], v[130:133], v[218:221], v[34:49]
	v_mfma_f32_32x32x16_bf16 v[34:49], v[126:129], v[222:225], v[34:49]
	v_mfma_f32_32x32x16_bf16 v[34:49], v[122:125], v[226:229], v[34:49]
	v_mfma_f32_32x32x16_bf16 v[34:49], v[118:121], v[230:233], v[34:49]
	ds_read_b64_tr_b16 v[218:219], v250 offset:0x600
	ds_read_b64_tr_b16 v[220:221], v250 offset:0xe00
	ds_read_b64_tr_b16 v[222:223], v250 offset:0x1600
	ds_read_b64_tr_b16 v[224:225], v250 offset:0x1e00
	ds_read_b64_tr_b16 v[226:227], v250 offset:0x2600
	ds_read_b64_tr_b16 v[228:229], v250 offset:0x2e00
	ds_read_b64_tr_b16 v[230:231], v250 offset:0x3600
	ds_read_b64_tr_b16 v[232:233], v250 offset:0x3e00
	s_waitcnt lgkmcnt(8)
	v_mfma_f32_32x32x16_bf16 v[18:33], v[130:133], v[202:205], v[18:33]
	v_mfma_f32_32x32x16_bf16 v[18:33], v[126:129], v[206:209], v[18:33]
	v_mfma_f32_32x32x16_bf16 v[18:33], v[122:125], v[210:213], v[18:33]
	v_mfma_f32_32x32x16_bf16 v[18:33], v[118:121], v[214:217], v[18:33]
	s_waitcnt lgkmcnt(0)
	v_mfma_f32_32x32x16_bf16 v[2:17], v[130:133], v[218:221], v[2:17]
	v_mfma_f32_32x32x16_bf16 v[2:17], v[126:129], v[222:225], v[2:17]
	v_mfma_f32_32x32x16_bf16 v[2:17], v[122:125], v[226:229], v[2:17]
	v_mfma_f32_32x32x16_bf16 v[2:17], v[118:121], v[230:233], v[2:17]
	s_and_b64 vcc, exec, s[6:7]
	s_cbranch_vccnz .LBB0_668
	s_waitcnt vmcnt(0)
.LBB0_668:
	s_and_b64 vcc, exec, s[2:3]
	s_barrier
	s_setprio 0
	s_cbranch_vccnz .LBB0_670
	s_mov_b32 m0, s89
	v_lshl_add_u64 v[118:119], s[52:53], 0, v[134:135]
	global_load_lds_dwordx4 v[118:119], off
	v_lshl_add_u64 v[118:119], s[52:53], 0, v[154:155]
	s_add_u32 s52, s52, 0x40000
	s_mov_b32 m0, s91
	s_addc_u32 s53, s53, 0
	global_load_lds_dwordx4 v[118:119], off
	v_lshl_add_u64 v[118:119], s[54:55], 0, v[144:145]
	s_add_u32 s54, s54, 0x100000
	s_mov_b32 m0, s92
	s_addc_u32 s55, s55, 0
	s_add_i32 s8, s89, s95
	global_load_lds_dwordx4 v[118:119], off
	v_lshl_add_u64 v[118:119], s[48:49], 0, v[142:143]
	s_add_i32 m0, s8, 0xc000
	s_nop 0
	global_load_lds_dwordx4 v[118:119], off
	v_lshl_add_u64 v[118:119], s[48:49], 0, v[152:153]
	s_add_i32 m0, s8, 0xc400
	s_add_u32 s48, s48, 0x40000
	global_load_lds_dwordx4 v[118:119], off
	s_addc_u32 s49, s49, 0

.LBB0_678:
	s_barrier
	s_setprio 3
	ds_read_b128 v[66:69], v161
	ds_read_b128 v[70:73], v161 offset:8192
	ds_read_b128 v[204:207], v163
	ds_read_b128 v[208:211], v163 offset:8192
	ds_read_b128 v[212:215], v165
	ds_read_b128 v[216:219], v165 offset:8192
	ds_read_b128 v[220:223], v167
	ds_read_b128 v[224:227], v167 offset:8192
	v_add_u32_e32 v252, s12, v185
	s_waitcnt lgkmcnt(0)
	v_mfma_f32_32x32x16_bf16 v[82:97], v[66:69], v[114:117], 0
	v_mfma_f32_32x32x16_bf16 v[66:81], v[70:73], v[114:117], 0
	v_mfma_f32_32x32x16_bf16 v[82:97], v[204:207], v[110:113], v[82:97]
	v_mfma_f32_32x32x16_bf16 v[66:81], v[208:211], v[110:113], v[66:81]
	ds_read_b128 v[204:207], v169 offset:8192
	ds_read_b128 v[208:211], v171
	ds_read_b128 v[228:231], v171 offset:8192
	ds_read_b128 v[232:235], v169
	ds_read_b128 v[236:239], v159
	v_mfma_f32_32x32x16_bf16 v[82:97], v[212:215], v[106:109], v[82:97]
	v_mfma_f32_32x32x16_bf16 v[66:81], v[216:219], v[106:109], v[66:81]
	v_mfma_f32_32x32x16_bf16 v[82:97], v[220:223], v[102:105], v[82:97]
	v_mfma_f32_32x32x16_bf16 v[66:81], v[224:227], v[102:105], v[66:81]
	ds_read_b128 v[212:215], v173
	ds_read_b128 v[216:219], v173 offset:8192
	ds_read_b128 v[220:223], v175
	ds_read_b128 v[224:227], v175 offset:8192
	ds_read_b128 v[240:243], v159 offset:1024
	ds_read_b128 v[244:247], v159 offset:2048
	s_waitcnt lgkmcnt(0)
	v_mfma_f32_32x32x16_bf16 v[82:97], v[232:235], v[98:101], v[82:97]
	v_mfma_f32_32x32x16_bf16 v[66:81], v[204:207], v[98:101], v[66:81]
	v_mfma_f32_32x32x16_bf16 v[82:97], v[208:211], v[236:239], v[82:97]
	v_mfma_f32_32x32x16_bf16 v[66:81], v[228:231], v[236:239], v[66:81]
	ds_read_b128 v[204:207], v178 offset:32768
	ds_read_b128 v[208:211], v178 offset:36864
	ds_read_b128 v[228:231], v180 offset:32768
	ds_read_b128 v[232:235], v180 offset:36864
	ds_read_b128 v[236:239], v159 offset:3072
	ds_read_b128 v[248:251], v159 offset:4096
	v_mfma_f32_32x32x16_bf16 v[82:97], v[212:215], v[240:243], v[82:97]
	v_mfma_f32_32x32x16_bf16 v[66:81], v[216:219], v[240:243], v[66:81]
	v_mfma_f32_32x32x16_bf16 v[82:97], v[220:223], v[244:247], v[82:97]
	v_mfma_f32_32x32x16_bf16 v[66:81], v[224:227], v[244:247], v[66:81]
	ds_read_b128 v[212:215], v182 offset:32768
	ds_read_b128 v[216:219], v182 offset:36864
	ds_read_b128 v[220:223], v184 offset:32768
	ds_read_b128 v[224:227], v184 offset:36864
	ds_read_b128 v[240:243], v159 offset:5120
	ds_read_b128 v[244:247], v159 offset:6144
	s_waitcnt lgkmcnt(0)
	v_mfma_f32_32x32x16_bf16 v[82:97], v[204:207], v[236:239], v[82:97]
	v_mfma_f32_32x32x16_bf16 v[66:81], v[208:211], v[236:239], v[66:81]
	v_mfma_f32_32x32x16_bf16 v[82:97], v[228:231], v[248:251], v[82:97]
	v_mfma_f32_32x32x16_bf16 v[66:81], v[232:235], v[248:251], v[66:81]
	v_mfma_f32_32x32x16_bf16 v[82:97], v[212:215], v[240:243], v[82:97]
	v_mfma_f32_32x32x16_bf16 v[66:81], v[216:219], v[240:243], v[66:81]
	v_mfma_f32_32x32x16_bf16 v[82:97], v[220:223], v[244:247], v[82:97]
	v_mfma_f32_32x32x16_bf16 v[66:81], v[224:227], v[244:247], v[66:81]
	ds_read_b64_tr_b16 v[204:205], v252 offset:0
	ds_read_b64_tr_b16 v[206:207], v252 offset:0x800
	ds_read_b64_tr_b16 v[208:209], v252 offset:0x1000
	ds_read_b64_tr_b16 v[210:211], v252 offset:0x1800
	ds_read_b64_tr_b16 v[212:213], v252 offset:0x2000
	ds_read_b64_tr_b16 v[214:215], v252 offset:0x2800
	ds_read_b64_tr_b16 v[216:217], v252 offset:0x3000
	ds_read_b64_tr_b16 v[218:219], v252 offset:0x3800
	ds_read_b64_tr_b16 v[220:221], v252 offset:0x200
	ds_read_b64_tr_b16 v[222:223], v252 offset:0xa00
	ds_read_b64_tr_b16 v[224:225], v252 offset:0x1200
	ds_read_b64_tr_b16 v[226:227], v252 offset:0x1a00
	ds_read_b64_tr_b16 v[228:229], v252 offset:0x2200
	ds_read_b64_tr_b16 v[230:231], v252 offset:0x2a00
	ds_read_b64_tr_b16 v[232:233], v252 offset:0x3200
	ds_read_b64_tr_b16 v[234:235], v252 offset:0x3a00
	s_waitcnt lgkmcnt(8)
	s_nop 0
	v_mfma_f32_32x32x16_bf16 v[50:65], v[130:133], v[204:207], v[50:65]
	v_mfma_f32_32x32x16_bf16 v[50:65], v[126:129], v[208:211], v[50:65]
	v_mfma_f32_32x32x16_bf16 v[50:65], v[122:125], v[212:215], v[50:65]
	v_mfma_f32_32x32x16_bf16 v[50:65], v[118:121], v[216:219], v[50:65]
	ds_read_b64_tr_b16 v[204:205], v252 offset:0x400
	ds_read_b64_tr_b16 v[206:207], v252 offset:0xc00
	ds_read_b64_tr_b16 v[208:209], v252 offset:0x1400
	ds_read_b64_tr_b16 v[210:211], v252 offset:0x1c00
	ds_read_b64_tr_b16 v[212:213], v252 offset:0x2400
	ds_read_b64_tr_b16 v[214:215], v252 offset:0x2c00
	ds_read_b64_tr_b16 v[216:217], v252 offset:0x3400
	ds_read_b64_tr_b16 v[218:219], v252 offset:0x3c00
	s_waitcnt lgkmcnt(8)
	v_mfma_f32_32x32x16_bf16 v[34:49], v[130:133], v[220:223], v[34:49]
	v_mfma_f32_32x32x16_bf16 v[34:49], v[126:129], v[224:227], v[34:49]
	v_mfma_f32_32x32x16_bf16 v[34:49], v[122:125], v[228:231], v[34:49]
	v_mfma_f32_32x32x16_bf16 v[34:49], v[118:121], v[232:235], v[34:49]
	ds_read_b64_tr_b16 v[220:221], v252 offset:0x600
	ds_read_b64_tr_b16 v[222:223], v252 offset:0xe00
	ds_read_b64_tr_b16 v[224:225], v252 offset:0x1600
	ds_read_b64_tr_b16 v[226:227], v252 offset:0x1e00
	ds_read_b64_tr_b16 v[228:229], v252 offset:0x2600
	ds_read_b64_tr_b16 v[230:231], v252 offset:0x2e00
	ds_read_b64_tr_b16 v[232:233], v252 offset:0x3600
	ds_read_b64_tr_b16 v[234:235], v252 offset:0x3e00
	s_waitcnt lgkmcnt(8)
	v_mfma_f32_32x32x16_bf16 v[18:33], v[130:133], v[204:207], v[18:33]
	v_mfma_f32_32x32x16_bf16 v[18:33], v[126:129], v[208:211], v[18:33]
	v_mfma_f32_32x32x16_bf16 v[18:33], v[122:125], v[212:215], v[18:33]
	v_mfma_f32_32x32x16_bf16 v[18:33], v[118:121], v[216:219], v[18:33]
	s_waitcnt lgkmcnt(0)
	v_mfma_f32_32x32x16_bf16 v[2:17], v[130:133], v[220:223], v[2:17]
	v_mfma_f32_32x32x16_bf16 v[2:17], v[126:129], v[224:227], v[2:17]
	v_mfma_f32_32x32x16_bf16 v[2:17], v[122:125], v[228:231], v[2:17]
	v_mfma_f32_32x32x16_bf16 v[2:17], v[118:121], v[232:235], v[2:17]
	s_and_b64 vcc, exec, s[6:7]
	s_cbranch_vccnz .LBB0_680
	s_waitcnt vmcnt(0)
.LBB0_680:
	s_and_b64 vcc, exec, s[2:3]
	s_barrier
	s_setprio 0
	s_cbranch_vccnz .LBB0_682
	v_lshl_add_u64 v[118:119], s[52:53], 0, v[134:135]
	s_add_i32 m0, s89, 0x4000
	s_nop 0
	global_load_lds_dwordx4 v[118:119], off
	s_add_i32 m0, s89, 0x4400
	v_lshl_add_u64 v[118:119], s[52:53], 0, v[154:155]
	s_add_u32 s52, s52, 0x40000
	global_load_lds_dwordx4 v[118:119], off
	s_addc_u32 s53, s53, 0
	s_add_i32 m0, s90, 0xa000
	v_lshl_add_u64 v[118:119], s[54:55], 0, v[144:145]
	s_add_u32 s54, s54, 0x100000
	s_addc_u32 s55, s55, 0
	s_add_i32 s8, s89, s94
	global_load_lds_dwordx4 v[118:119], off
	v_lshl_add_u64 v[118:119], s[48:49], 0, v[142:143]
	s_add_i32 m0, s8, 0xc000
	s_nop 0
	global_load_lds_dwordx4 v[118:119], off
	v_lshl_add_u64 v[118:119], s[48:49], 0, v[152:153]
	s_add_i32 m0, s8, 0xc400
	s_add_u32 s48, s48, 0x40000
	global_load_lds_dwordx4 v[118:119], off
	s_addc_u32 s49, s49, 0
